# v21 + prologue load de-serialisation: the 32 exec-masked w_in merge-gate loads per P0 item issued back-to-back with counted vmcnt waits instead of load/wait(0)/ds_write one at a time
# speedup vs baseline: 1.0079x; 1.0035x over previous
; #define LAS __attribute__((address_space(3)))
; template <int MAP> __device__ __forceinline__ float p0_item8(const float* W, int K, int N, unsigned char* W8, LAS float* scr, int item, int lane, float sW, bool i8 = false) {
;     const int nblk = (N + 31) / 32, kb = item / nblk, nb = item % nblk, k0 = 64 * kb, n0 = 32 * nb;
;     const int nn = n0 + (lane & 31); const bool okr = nn < N;
;     float mx = 0.f; const bool cnt = !(MAP == 4 && nn < 9232);
; #pragma unroll
;     for (int i = 0; i < 32; ++i) { const int kk = 2 * i + (lane >> 5); const float v = okr ? W[(size_t)(k0 + kk) * N + nn] : 0.f; scr[kk * 33 + (lane & 31)] = v; mx = fmaxf(mx, cnt ? fabsf(v) : 0.f); }
.LBB0_65:
	s_or_b64 exec, exec, s[36:37]
	s_and_saveexec_b64 s[36:37], vcc
	s_cbranch_execz .LBB0_67
	v_or_b32_e32 v6, s29, v31
	v_mul_u32_u24_e32 v6, 0xf040, v6
	v_lshl_add_u64 v[20:21], v[14:15], 0, v[6:7]
	global_load_dword v18, v[20:21], off
.LBB0_67:
	s_or_b64 exec, exec, s[36:37]
	v_mov_b32_e32 v20, 0
	v_mov_b32_e32 v21, 0
	s_and_saveexec_b64 s[36:37], vcc
	s_cbranch_execz .LBB0_69
	v_or_b32_e32 v6, s29, v32
	v_mul_u32_u24_e32 v6, 0xf040, v6
	v_lshl_add_u64 v[22:23], v[14:15], 0, v[6:7]
	global_load_dword v21, v[22:23], off
.LBB0_69:
	s_or_b64 exec, exec, s[36:37]
	s_and_saveexec_b64 s[36:37], vcc
	s_cbranch_execz .LBB0_71
	v_or_b32_e32 v6, s29, v34
	v_mul_u32_u24_e32 v6, 0xf040, v6
	v_lshl_add_u64 v[22:23], v[14:15], 0, v[6:7]
	global_load_dword v20, v[22:23], off
.LBB0_71:
	s_or_b64 exec, exec, s[36:37]
	v_mov_b32_e32 v22, 0
	v_mov_b32_e32 v23, 0
	s_and_saveexec_b64 s[36:37], vcc
	s_cbranch_execz .LBB0_73
	v_or_b32_e32 v6, s29, v35
	v_mul_u32_u24_e32 v6, 0xf040, v6
	v_lshl_add_u64 v[24:25], v[14:15], 0, v[6:7]
	global_load_dword v23, v[24:25], off
.LBB0_73:
	s_or_b64 exec, exec, s[36:37]
	s_and_saveexec_b64 s[36:37], vcc
	s_cbranch_execz .LBB0_75
	v_or_b32_e32 v6, s29, v37
	v_mul_u32_u24_e32 v6, 0xf040, v6
	v_lshl_add_u64 v[24:25], v[14:15], 0, v[6:7]
	global_load_dword v22, v[24:25], off
.LBB0_75:
	s_or_b64 exec, exec, s[36:37]
	v_mov_b32_e32 v24, 0
	v_mov_b32_e32 v25, 0
	s_and_saveexec_b64 s[36:37], vcc
	s_cbranch_execz .LBB0_77
	v_or_b32_e32 v6, s29, v38
	v_mul_u32_u24_e32 v6, 0xf040, v6
	v_lshl_add_u64 v[26:27], v[14:15], 0, v[6:7]
	global_load_dword v25, v[26:27], off
.LBB0_77:
	s_or_b64 exec, exec, s[36:37]
	s_and_saveexec_b64 s[36:37], vcc
	s_cbranch_execz .LBB0_79
	v_or_b32_e32 v6, s29, v40
	v_mul_u32_u24_e32 v6, 0xf040, v6
	v_lshl_add_u64 v[26:27], v[14:15], 0, v[6:7]
	global_load_dword v24, v[26:27], off
.LBB0_79:
	s_or_b64 exec, exec, s[36:37]
	v_mov_b32_e32 v26, 0
	v_mov_b32_e32 v27, 0
	s_and_saveexec_b64 s[36:37], vcc
	s_cbranch_execz .LBB0_81
	v_or_b32_e32 v6, s29, v41
	v_mul_u32_u24_e32 v6, 0xf040, v6
	v_lshl_add_u64 v[28:29], v[14:15], 0, v[6:7]
	global_load_dword v27, v[28:29], off
.LBB0_81:
	s_or_b64 exec, exec, s[36:37]
	s_and_saveexec_b64 s[36:37], vcc
	s_cbranch_execz .LBB0_83
	v_or_b32_e32 v6, s29, v43
	v_mul_u32_u24_e32 v6, 0xf040, v6
	v_lshl_add_u64 v[28:29], v[14:15], 0, v[6:7]
	global_load_dword v26, v[28:29], off
.LBB0_83:
	s_or_b64 exec, exec, s[36:37]
	v_mov_b32_e32 v28, 0
	v_mov_b32_e32 v29, 0
	s_and_saveexec_b64 s[36:37], vcc
	s_cbranch_execz .LBB0_85
	v_or_b32_e32 v6, s29, v44
	v_mul_u32_u24_e32 v6, 0xf040, v6
	v_lshl_add_u64 v[98:99], v[14:15], 0, v[6:7]
	global_load_dword v29, v[98:99], off
.LBB0_85:
	s_or_b64 exec, exec, s[36:37]
	s_and_saveexec_b64 s[36:37], vcc
	s_cbranch_execz .LBB0_87
	v_or_b32_e32 v6, s29, v46
	v_mul_u32_u24_e32 v6, 0xf040, v6
	v_lshl_add_u64 v[98:99], v[14:15], 0, v[6:7]
	global_load_dword v28, v[98:99], off
.LBB0_87:
	s_or_b64 exec, exec, s[36:37]
	v_mov_b32_e32 v97, 0
	v_mov_b32_e32 v98, 0
	s_and_saveexec_b64 s[36:37], vcc
	s_cbranch_execz .LBB0_89
	v_or_b32_e32 v6, s29, v47
	v_mul_u32_u24_e32 v6, 0xf040, v6
	v_lshl_add_u64 v[98:99], v[14:15], 0, v[6:7]
	global_load_dword v98, v[98:99], off
.LBB0_89:
	s_or_b64 exec, exec, s[36:37]
	s_and_saveexec_b64 s[36:37], vcc
	s_cbranch_execz .LBB0_91
	v_or_b32_e32 v6, s29, v49
	v_mul_u32_u24_e32 v6, 0xf040, v6
	v_lshl_add_u64 v[100:101], v[14:15], 0, v[6:7]
	global_load_dword v97, v[100:101], off
.LBB0_91:
	s_or_b64 exec, exec, s[36:37]
	v_mov_b32_e32 v99, 0
	v_mov_b32_e32 v100, 0
	s_and_saveexec_b64 s[36:37], vcc
	s_cbranch_execz .LBB0_93
	v_or_b32_e32 v6, s29, v50
	v_mul_u32_u24_e32 v6, 0xf040, v6
	v_lshl_add_u64 v[100:101], v[14:15], 0, v[6:7]
	global_load_dword v100, v[100:101], off
.LBB0_93:
	s_or_b64 exec, exec, s[36:37]
	s_and_saveexec_b64 s[36:37], vcc
	s_cbranch_execz .LBB0_95
	v_or_b32_e32 v6, s29, v52
	v_mul_u32_u24_e32 v6, 0xf040, v6
	v_lshl_add_u64 v[102:103], v[14:15], 0, v[6:7]
	global_load_dword v99, v[102:103], off
.LBB0_95:
	s_or_b64 exec, exec, s[36:37]
	v_mov_b32_e32 v101, 0
	v_mov_b32_e32 v102, 0
	s_and_saveexec_b64 s[36:37], vcc
	s_cbranch_execz .LBB0_97
	v_or_b32_e32 v6, s29, v53
	v_mul_u32_u24_e32 v6, 0xf040, v6
	v_lshl_add_u64 v[102:103], v[14:15], 0, v[6:7]
	global_load_dword v102, v[102:103], off
.LBB0_97:
	s_or_b64 exec, exec, s[36:37]
	s_and_saveexec_b64 s[36:37], vcc
	s_cbranch_execz .LBB0_99
	v_or_b32_e32 v6, s29, v55
	v_mul_u32_u24_e32 v6, 0xf040, v6
	v_lshl_add_u64 v[104:105], v[14:15], 0, v[6:7]
	global_load_dword v101, v[104:105], off
.LBB0_99:
	s_or_b64 exec, exec, s[36:37]
	v_mov_b32_e32 v103, 0
	v_mov_b32_e32 v104, 0
	s_and_saveexec_b64 s[36:37], vcc
	s_cbranch_execz .LBB0_101
	v_or_b32_e32 v6, s29, v56
	v_mul_u32_u24_e32 v6, 0xf040, v6
	v_lshl_add_u64 v[104:105], v[14:15], 0, v[6:7]
	global_load_dword v104, v[104:105], off
.LBB0_101:
	s_or_b64 exec, exec, s[36:37]
	s_and_saveexec_b64 s[36:37], vcc
	s_cbranch_execz .LBB0_103
	v_or_b32_e32 v6, s29, v76
	v_mul_u32_u24_e32 v6, 0xf040, v6
	v_lshl_add_u64 v[106:107], v[14:15], 0, v[6:7]
	global_load_dword v103, v[106:107], off
.LBB0_103:
	s_or_b64 exec, exec, s[36:37]
	v_mov_b32_e32 v105, 0
	v_mov_b32_e32 v106, 0
	s_and_saveexec_b64 s[36:37], vcc
	s_cbranch_execz .LBB0_105
	v_or_b32_e32 v6, s29, v77
	v_mul_u32_u24_e32 v6, 0xf040, v6
	v_lshl_add_u64 v[106:107], v[14:15], 0, v[6:7]
	global_load_dword v106, v[106:107], off
.LBB0_105:
	s_or_b64 exec, exec, s[36:37]
	s_and_saveexec_b64 s[36:37], vcc
	s_cbranch_execz .LBB0_107
	v_or_b32_e32 v6, s29, v78
	v_mul_u32_u24_e32 v6, 0xf040, v6
	v_lshl_add_u64 v[108:109], v[14:15], 0, v[6:7]
	global_load_dword v105, v[108:109], off
; #define GAS __attribute__((address_space(1)))
; #define LAS __attribute__((address_space(3)))
; #define LDS_WAIT() asm volatile("s_waitcnt lgkmcnt(0)" ::: "memory")
; __device__ __forceinline__ unsigned pk4_fp8(float a, float b, float c, float d) { int w = 0; w = __builtin_amdgcn_cvt_pk_fp8_f32(a, b, w, false); w = __builtin_amdgcn_cvt_pk_fp8_f32(c, d, w, true); return (unsigned)w; }
; __device__ __forceinline__ float clamp127(float v) { return __builtin_amdgcn_fmed3f(v, -127.0f, 127.0f); }
; template <int MAP> __device__ __forceinline__ float p0_item8(const float* W, int K, int N, unsigned char* W8, LAS float* scr, int item, int lane, float sW, bool i8 = false) {
;     ...
;     for (int i = 0; i < 32; ++i) { const int kk = 2 * i + (lane >> 5); const float v = okr ? W[(size_t)(k0 + kk) * N + nn] : 0.f; scr[kk * 33 + (lane & 31)] = v; mx = fmaxf(mx, cnt ? fabsf(v) : 0.f); }
;     LDS_WAIT(); asm volatile("" ::: "memory");
;     const int c = lane & 7;
; #pragma unroll
;     for (int j = 0; j < 4; ++j) { const int n = (lane >> 3) + 8 * j; const LAS float* s = scr + (8 * c) * 33 + n;
;         v2u o; if (i8) { o.x = pk4_i8(clamp127(s[0 * 33] * sW), clamp127(s[1 * 33] * sW), clamp127(s[2 * 33] * sW), clamp127(s[3 * 33] * sW)); o.y = pk4_i8(clamp127(s[4 * 33] * sW), clamp127(s[5 * 33] * sW), clamp127(s[6 * 33] * sW), clamp127(s[7 * 33] * sW)); }
;         else { o.x = pk4_fp8(s[0 * 33] * sW, s[1 * 33] * sW, s[2 * 33] * sW, s[3 * 33] * sW); o.y = pk4_fp8(s[4 * 33] * sW, s[5 * 33] * sW, s[6 * 33] * sW, s[7 * 33] * sW); }
;         if (n0 + n < N && !(MAP == 4 && n0 + n < 9232)) __builtin_nontemporal_store(o, (GAS v2u*)(W8 + (size_t)dest_row<MAP>(n0 + n) * K + k0 + 8 * c)); }
.LBB0_107:
	s_or_b64 exec, exec, s[36:37]
	v_mov_b32_e32 v107, 0
	v_mov_b32_e32 v108, 0
	s_and_saveexec_b64 s[36:37], vcc
	s_cbranch_execz .LBB0_109
	v_or_b32_e32 v6, s29, v79
	v_mul_u32_u24_e32 v6, 0xf040, v6
	v_lshl_add_u64 v[108:109], v[14:15], 0, v[6:7]
	global_load_dword v108, v[108:109], off
.LBB0_109:
	s_or_b64 exec, exec, s[36:37]
	s_and_saveexec_b64 s[36:37], vcc
	s_cbranch_execz .LBB0_111
	v_or_b32_e32 v6, s29, v80
	v_mul_u32_u24_e32 v6, 0xf040, v6
	v_lshl_add_u64 v[110:111], v[14:15], 0, v[6:7]
	global_load_dword v107, v[110:111], off
.LBB0_111:
	s_or_b64 exec, exec, s[36:37]
	v_mov_b32_e32 v109, 0
	v_mov_b32_e32 v110, 0
	s_and_saveexec_b64 s[36:37], vcc
	s_cbranch_execz .LBB0_113
	v_or_b32_e32 v6, s29, v81
	v_mul_u32_u24_e32 v6, 0xf040, v6
	v_lshl_add_u64 v[110:111], v[14:15], 0, v[6:7]
	global_load_dword v110, v[110:111], off
.LBB0_113:
	s_or_b64 exec, exec, s[36:37]
	s_and_saveexec_b64 s[36:37], vcc
	s_cbranch_execz .LBB0_115
	v_or_b32_e32 v6, s29, v82
	v_mul_u32_u24_e32 v6, 0xf040, v6
	v_lshl_add_u64 v[112:113], v[14:15], 0, v[6:7]
	global_load_dword v109, v[112:113], off
.LBB0_115:
	s_or_b64 exec, exec, s[36:37]
	v_mov_b32_e32 v111, 0
	v_mov_b32_e32 v112, 0
	s_and_saveexec_b64 s[36:37], vcc
	s_cbranch_execz .LBB0_117
	v_or_b32_e32 v6, s29, v83
	v_mul_u32_u24_e32 v6, 0xf040, v6
	v_lshl_add_u64 v[112:113], v[14:15], 0, v[6:7]
	global_load_dword v112, v[112:113], off
.LBB0_117:
	s_or_b64 exec, exec, s[36:37]
	s_and_saveexec_b64 s[36:37], vcc
	s_cbranch_execz .LBB0_119
	v_or_b32_e32 v6, s29, v84
	v_mul_u32_u24_e32 v6, 0xf040, v6
	v_lshl_add_u64 v[114:115], v[14:15], 0, v[6:7]
	global_load_dword v111, v[114:115], off
.LBB0_119:
	s_or_b64 exec, exec, s[36:37]
	v_mov_b32_e32 v113, 0
	v_mov_b32_e32 v114, 0
	s_and_saveexec_b64 s[36:37], vcc
	s_cbranch_execz .LBB0_121
	v_or_b32_e32 v6, s29, v85
	v_mul_u32_u24_e32 v6, 0xf040, v6
	v_lshl_add_u64 v[114:115], v[14:15], 0, v[6:7]
	global_load_dword v114, v[114:115], off
.LBB0_121:
	s_or_b64 exec, exec, s[36:37]
	s_and_saveexec_b64 s[36:37], vcc
	s_cbranch_execz .LBB0_123
	v_or_b32_e32 v6, s29, v86
	v_mul_u32_u24_e32 v6, 0xf040, v6
	v_lshl_add_u64 v[118:119], v[14:15], 0, v[6:7]
	global_load_dword v113, v[118:119], off
.LBB0_123:
	s_or_b64 exec, exec, s[36:37]
	v_mov_b32_e32 v116, 0
	v_mov_b32_e32 v115, 0
	s_and_saveexec_b64 s[36:37], vcc
	s_cbranch_execz .LBB0_125
	v_or_b32_e32 v6, s29, v87
	v_mul_u32_u24_e32 v6, 0xf040, v6
	v_lshl_add_u64 v[118:119], v[14:15], 0, v[6:7]
	global_load_dword v115, v[118:119], off
.LBB0_125:
	s_or_b64 exec, exec, s[36:37]
	s_and_saveexec_b64 s[36:37], vcc
	s_cbranch_execz .LBB0_127
	v_or_b32_e32 v6, s29, v88
	v_mul_u32_u24_e32 v6, 0xf040, v6
	v_lshl_add_u64 v[14:15], v[14:15], 0, v[6:7]
	global_load_dword v116, v[14:15], off
.LBB0_127:
	s_or_b64 exec, exec, s[36:37]
	v_add_u32_e32 v6, v13, v30
	s_waitcnt vmcnt(31)
	ds_write_b32 v6, v19
	s_waitcnt vmcnt(30)
	ds_write_b32 v63, v18
	v_add_u32_e32 v6, v13, v33
	s_waitcnt vmcnt(29)
	ds_write_b32 v6, v21
	s_waitcnt vmcnt(28)
	ds_write_b32 v64, v20
	v_add_u32_e32 v6, v13, v36
	s_waitcnt vmcnt(27)
	ds_write_b32 v6, v23
	s_waitcnt vmcnt(26)
	ds_write_b32 v65, v22
	v_add_u32_e32 v6, v13, v39
	s_waitcnt vmcnt(25)
	ds_write_b32 v6, v25
	s_waitcnt vmcnt(24)
	ds_write_b32 v67, v24
	v_add_u32_e32 v6, v13, v42
	s_waitcnt vmcnt(23)
	ds_write_b32 v6, v27
	s_waitcnt vmcnt(22)
	ds_write_b32 v68, v26
	v_add_u32_e32 v6, v13, v45
	s_waitcnt vmcnt(21)
	ds_write_b32 v6, v29
	s_waitcnt vmcnt(20)
	ds_write_b32 v69, v28
	v_add_u32_e32 v6, v13, v48
	s_waitcnt vmcnt(19)
	ds_write_b32 v6, v98
	s_waitcnt vmcnt(18)
	ds_write_b32 v70, v97
	v_add_u32_e32 v6, v13, v51
	s_waitcnt vmcnt(17)
	ds_write_b32 v6, v100
	s_waitcnt vmcnt(16)
	ds_write_b32 v71, v99
	v_add_u32_e32 v6, v13, v54
	s_waitcnt vmcnt(15)
	ds_write_b32 v6, v102
	s_waitcnt vmcnt(14)
	ds_write_b32 v72, v101
	v_add_u32_e32 v6, v13, v57
	s_waitcnt vmcnt(13)
	ds_write_b32 v6, v104
	s_waitcnt vmcnt(12)
	ds_write_b32 v73, v103
	v_add_u32_e32 v6, v13, v58
	s_waitcnt vmcnt(11)
	ds_write_b32 v6, v106
	s_waitcnt vmcnt(10)
	ds_write_b32 v74, v105
	v_add_u32_e32 v6, v13, v59
	s_waitcnt vmcnt(9)
	ds_write_b32 v6, v108
	s_waitcnt vmcnt(8)
	ds_write_b32 v75, v107
	v_add_u32_e32 v117, v13, v60
	s_waitcnt vmcnt(7)
	ds_write_b32 v117, v110
	s_waitcnt vmcnt(6)
	ds_write_b32 v117, v109 offset:264
	s_waitcnt vmcnt(5)
	ds_write_b32 v117, v112 offset:528
	s_waitcnt vmcnt(4)
	ds_write_b32 v117, v111 offset:792
	s_waitcnt vmcnt(3)
	ds_write_b32 v117, v114 offset:1056
	s_waitcnt vmcnt(2)
	ds_write_b32 v117, v113 offset:1320
	s_waitcnt vmcnt(1)
	ds_write_b32 v117, v115 offset:1584
	s_waitcnt vmcnt(0)
	ds_write_b32 v117, v116 offset:1848
	s_waitcnt lgkmcnt(0)
	s_add_u32 s36, s59, s29
	s_addc_u32 s37, s61, 0
	v_lshl_add_u64 v[14:15], s[36:37], 0, v[4:5]
	s_mov_b64 s[36:37], 0x6a00000
	s_cmpk_lt_u32 s11, 0x121
	v_lshl_add_u64 v[14:15], v[14:15], 0, s[36:37]
	s_cbranch_scc1 .LBB0_129
	ds_read2_b32 v[118:119], v62 offset0:66 offset1:74
	ds_read2_b32 v[120:121], v62 offset0:99 offset1:107
	ds_read2_b32 v[122:123], v62 offset1:8
	ds_read2_b32 v[124:125], v62 offset0:33 offset1:41
	ds_read2_b32 v[130:131], v62 offset0:132 offset1:140
	ds_read2_b32 v[132:133], v62 offset0:165 offset1:173
	v_or_b32_e32 v6, s12, v61
	v_lshlrev_b32_e32 v6, 11, v6
	v_lshl_add_u64 v[126:127], v[14:15], 0, v[6:7]
	s_waitcnt lgkmcnt(5)
	v_mul_f32_e32 v6, v11, v118
	s_waitcnt lgkmcnt(4)
	v_mul_f32_e32 v117, v11, v120
	s_waitcnt lgkmcnt(3)
	v_mul_f32_e32 v118, v11, v122
	s_waitcnt lgkmcnt(2)
	v_mul_f32_e32 v120, v11, v124
	v_mov_b32_e32 v128, v7
	ds_read2_b32 v[134:135], v62 offset0:198 offset1:206
	ds_read2_b32 v[136:137], v62 offset0:231 offset1:239
	v_cvt_pk_fp8_f32 v128, v118, v120
	s_waitcnt lgkmcnt(3)
	v_mul_f32_e32 v118, v11, v130
	s_waitcnt lgkmcnt(2)
	v_mul_f32_e32 v120, v11, v132
	v_mov_b32_e32 v129, v7
	v_cvt_pk_fp8_f32 v129, v118, v120
	v_cvt_pk_fp8_f32 v128, v6, v117 op_sel:[0,0,1]
	s_waitcnt lgkmcnt(1)
	v_mul_f32_e32 v6, v11, v134
	s_waitcnt lgkmcnt(0)
	v_mul_f32_e32 v117, v11, v136
	v_cvt_pk_fp8_f32 v129, v6, v117 op_sel:[0,0,1]
	s_mov_b32 s11, 0xfedf8000
	v_add_co_u32_e32 v126, vcc, s11, v126
	v_or_b32_e32 v6, s12, v89
	s_nop 0
	v_addc_co_u32_e32 v127, vcc, -1, v127, vcc
	v_lshlrev_b32_e32 v6, 11, v6
	global_store_dwordx2 v[126:127], v[128:129], off nt
	v_lshl_add_u64 v[126:127], v[14:15], 0, v[6:7]
	v_mul_f32_e32 v6, v11, v119
	v_mul_f32_e32 v119, v11, v123
	v_mul_f32_e32 v120, v11, v125
	v_mov_b32_e32 v118, v7
	v_mul_f32_e32 v117, v11, v121
	v_cvt_pk_fp8_f32 v118, v119, v120
	v_mul_f32_e32 v120, v11, v131
	v_mul_f32_e32 v121, v11, v133
	v_mov_b32_e32 v119, v7
	v_cvt_pk_fp8_f32 v119, v120, v121
	v_cvt_pk_fp8_f32 v118, v6, v117 op_sel:[0,0,1]
	v_mul_f32_e32 v6, v11, v135
	v_mul_f32_e32 v117, v11, v137
	v_cvt_pk_fp8_f32 v119, v6, v117 op_sel:[0,0,1]
	v_add_co_u32_e32 v120, vcc, 0xfedf8000, v126
	s_nop 1
	v_addc_co_u32_e32 v121, vcc, -1, v127, vcc
	global_store_dwordx2 v[120:121], v[118:119], off nt
